# LayerNorm loop: next iteration's four rows requested a quarter into the current one, row loads no longer queue behind the stores
# speedup vs baseline: 1.0063x; 1.0063x over previous
.LBB0_35:
	s_mov_b32 s44, 0
	s_add_i32 s2, s44, s76
	s_waitcnt vmcnt(0)
	v_mbcnt_lo_u32_b32 v0, -1, 0
	v_mbcnt_hi_u32_b32 v0, -1, v0
	s_add_i32 s18, s44, s69
	v_lshl_add_u32 v176, s2, 6, v0
	s_add_i32 s82, s44, s72
	v_readfirstlane_b32 s2, v176
	s_ashr_i32 s6, s2, 6
	v_readlane_b32 s4, v254, 11
	s_cmp_gt_u32 s4, 16
	s_cselect_b64 s[2:3], -1, 0
	s_cmp_lt_u32 s4, 17
	s_cselect_b64 s[10:11], -1, 0
	s_and_b64 s[4:5], s[10:11], exec
	s_mov_b32 s4, 0x12000
	s_cselect_b32 s4, s4, 0x10000
	s_lshl_b32 s5, s82, 3
	s_abs_i32 s7, s5
	v_cvt_f32_u32_e32 v1, s7
	s_mov_b32 s14, s18
	v_writelane_b32 v254, s14, 41
	s_lshl_b32 s13, s18, 3
	v_rcp_iflag_f32_e32 v1, v1
	v_writelane_b32 v254, s15, 42
	s_add_i32 s6, s6, s13
	s_sub_i32 s13, 0, s7
	v_mul_f32_e32 v1, 0x4f7ffffe, v1
	v_cvt_u32_f32_e32 v1, v1
	s_add_i32 s12, s4, s5
	s_add_i32 s12, s12, -1
	s_xor_b32 s5, s12, s5
	v_readfirstlane_b32 s14, v1
	s_mul_i32 s13, s13, s14
	s_mul_hi_u32 s13, s14, s13
	s_abs_i32 s12, s12
	s_add_i32 s14, s14, s13
	s_mul_hi_u32 s13, s12, s14
	s_mul_i32 s14, s13, s7
	s_sub_i32 s12, s12, s14
	s_ashr_i32 s5, s5, 31
	s_add_i32 s14, s13, 1
	s_sub_i32 s15, s12, s7
	s_cmp_ge_u32 s12, s7
	s_cselect_b32 s13, s14, s13
	s_cselect_b32 s12, s15, s12
	s_add_i32 s14, s13, 1
	s_cmp_ge_u32 s12, s7
	s_cselect_b32 s7, s14, s13
	s_xor_b32 s7, s7, s5
	s_sub_i32 s5, s7, s5
	s_mul_i32 s56, s5, s6
	s_add_i32 s5, s56, s5
	s_min_i32 s57, s5, s4
	s_cmp_ge_i32 s56, s57
	s_mov_b32 s54, 0x800000
	s_cbranch_scc1 .LBB0_134
	v_readlane_b32 s28, v254, 11
	s_cmp_lg_u32 s28, 21
	s_cselect_b64 s[6:7], -1, 0
	s_cmp_eq_u32 s28, 21
	s_cselect_b64 s[12:13], -1, 0
	s_cmp_eq_u32 s28, 17
	s_cselect_b64 s[14:15], -1, 0
	s_lshl_b64 s[4:5], s[44:45], 3
	s_add_u32 s22, s70, s4
	v_readlane_b32 s24, v253, 62
	s_addc_u32 s23, s71, s5
	v_readlane_b32 s26, v254, 0
	v_readlane_b32 s27, v254, 1
	s_add_u32 s4, s26, s44
	s_addc_u32 s5, s27, 0
	s_lshl_b64 s[18:19], s[44:45], 2
	v_readlane_b32 s25, v253, 63
	s_add_u32 s58, s24, s18
	s_addc_u32 s59, s25, s19
	s_cmp_eq_u32 s28, 10
	s_cselect_b64 s[18:19], -1, 0
	s_and_b64 s[20:21], s[18:19], exec
	s_movk_i32 s20, 0x400
	s_cselect_b32 s60, s20, 0x1000
	s_cselect_b32 s61, 0, 0xc00
	s_or_b64 s[12:13], s[18:19], s[12:13]
	s_and_b64 s[18:19], s[12:13], exec
	s_cselect_b32 s18, 64, 48
	s_add_u32 s18, s22, s18
	s_addc_u32 s19, s23, 0
	s_load_dwordx2 s[18:19], s[18:19], 0x0
	s_and_b64 s[10:11], s[10:11], exec
	s_cselect_b32 s20, 0, 0x1000
	v_and_b32_e32 v34, 63, v0
	v_lshlrev_b32_e32 v192, 5, v34
	s_waitcnt lgkmcnt(0)
	s_add_u32 s10, s18, s20
	s_addc_u32 s11, s19, 0
	s_and_b64 s[12:13], s[12:13], exec
	s_cselect_b32 s12, 0x48, 56
	s_add_u32 s12, s22, s12
	s_addc_u32 s13, s23, 0
	s_load_dwordx2 s[12:13], s[12:13], 0x0
	v_xor_b32_e32 v32, 1, v229
	v_cmp_lt_i32_e32 vcc, v32, v231
	v_mov_b32_e32 v33, v193
	v_mov_b32_e32 v62, 0
	s_waitcnt lgkmcnt(0)
	s_add_u32 s12, s12, s20
	s_addc_u32 s13, s13, 0
	global_load_dwordx4 v[0:3], v192, s[10:11] offset:16
	global_load_dwordx4 v[4:7], v192, s[10:11]
	global_load_dwordx4 v[8:11], v192, s[12:13] offset:16
	global_load_dwordx4 v[12:15], v192, s[12:13]
	global_load_dwordx4 v[16:19], v192, s[10:11] offset:2064
	global_load_dwordx4 v[20:23], v192, s[10:11] offset:2048
	global_load_dwordx4 v[24:27], v192, s[12:13] offset:2064
	global_load_dwordx4 v[28:31], v192, s[12:13] offset:2048
	v_cndmask_b32_e32 v32, v229, v32, vcc
	v_lshlrev_b32_e32 v109, 2, v32
	v_xor_b32_e32 v32, 2, v229
	v_cmp_lt_i32_e32 vcc, v32, v231
	s_cmp_eq_u32 s28, 6
	s_cselect_b64 s[10:11], -1, 0
	v_cndmask_b32_e32 v32, v229, v32, vcc
	v_lshlrev_b32_e32 v121, 2, v32
	v_xor_b32_e32 v32, 4, v229
	v_cmp_lt_i32_e32 vcc, v32, v231
	s_and_b64 s[12:13], s[10:11], exec
	s_mov_b32 s12, 0x44d4000
	v_cndmask_b32_e32 v32, v229, v32, vcc
	v_lshlrev_b32_e32 v122, 2, v32
	v_xor_b32_e32 v32, 8, v229
	v_cmp_lt_i32_e32 vcc, v32, v231
	s_cselect_b32 s12, s12, 0x459a000
	s_or_b64 s[10:11], s[10:11], s[14:15]
	v_cndmask_b32_e32 v32, v229, v32, vcc
	v_lshlrev_b32_e32 v123, 2, v32
	v_xor_b32_e32 v32, 16, v229
	v_cmp_lt_i32_e32 vcc, v32, v231
	s_add_u32 s62, s4, 0x38260000
	s_addc_u32 s63, s5, 0
	v_cndmask_b32_e32 v32, v229, v32, vcc
	v_lshlrev_b32_e32 v124, 2, v32
	v_xor_b32_e32 v32, 32, v229
	s_add_u32 s64, s4, 0x3d2e4000
	v_cmp_lt_i32_e32 vcc, v32, v231
	s_addc_u32 s65, s5, 0
	s_add_u32 s14, s4, s12
	v_cndmask_b32_e32 v32, v229, v32, vcc
	v_lshlrev_b32_e32 v125, 2, v32
	v_lshlrev_b32_e32 v32, 4, v34
	s_addc_u32 s15, s5, 0
	v_lshl_add_u64 v[32:33], s[4:5], 0, v[32:33]
	s_mov_b64 s[4:5], 0x4660000
	v_lshl_add_u64 v[110:111], v[32:33], 0, s[4:5]
	v_cmp_eq_u32_e32 vcc, 0, v34
	s_mov_b64 s[4:5], 0x16660000
	v_lshlrev_b32_e32 v108, 3, v34
	s_mov_b32 s68, -1
	s_and_b64 s[12:13], s[6:7], vcc
	v_lshl_add_u64 v[112:113], s[14:15], 0, v[192:193]
	v_lshl_add_u64 v[114:115], v[32:33], 0, s[4:5]
	v_mov_b32_e32 v63, v62
	v_mov_b32_e32 v54, v62
	v_mov_b32_e32 v55, v62
	v_mov_b32_e32 v60, v62
	v_mov_b32_e32 v61, v62
	v_mov_b32_e32 v52, v62
	v_mov_b32_e32 v53, v62
	v_mov_b32_e32 v58, v62
	v_mov_b32_e32 v59, v62
	v_mov_b32_e32 v50, v62
	v_mov_b32_e32 v51, v62
	v_mov_b32_e32 v56, v62
	v_mov_b32_e32 v57, v62
	v_mov_b32_e32 v48, v62
	v_mov_b32_e32 v49, v62
	v_mov_b32_e32 v38, v62
	v_mov_b32_e32 v39, v62
	v_mov_b32_e32 v46, v62
	v_mov_b32_e32 v47, v62
	v_mov_b32_e32 v36, v62
	v_mov_b32_e32 v37, v62
	v_mov_b32_e32 v44, v62
	v_mov_b32_e32 v45, v62
	v_mov_b32_e32 v34, v62
	v_mov_b32_e32 v35, v62
	v_mov_b32_e32 v42, v62
	v_mov_b32_e32 v43, v62
	v_mov_b32_e32 v32, v62
	v_mov_b32_e32 v33, v62
	v_mov_b32_e32 v40, v62
	v_mov_b32_e32 v41, v62
	s_add_i32 s98, s56, 0
	s_ashr_i32 s99, s98, 11
	s_mulk_i32 s99, 0x900
	s_and_b32 s100, s98, 0x7ff
	s_add_i32 s99, s99, s100
	s_addk_i32 s99, 0x100
	s_and_b64 s[100:101], s[2:3], exec
	s_cselect_b32 s98, s99, s98
	s_ashr_i32 s99, s98, 31
	s_lshl_b64 s[98:99], s[98:99], 11
	v_lshl_add_u64 v[168:169], v[110:111], 0, s[98:99]
	global_load_dwordx4 v[136:139], v[168:169], off
	global_load_dwordx4 v[140:143], v[168:169], off offset:1024
	s_add_i32 s98, s56, 1
	s_ashr_i32 s99, s98, 11
	s_mulk_i32 s99, 0x900
	s_and_b32 s100, s98, 0x7ff
	s_add_i32 s99, s99, s100
	s_addk_i32 s99, 0x100
	s_and_b64 s[100:101], s[2:3], exec
	s_cselect_b32 s98, s99, s98
	s_ashr_i32 s99, s98, 31
	s_lshl_b64 s[98:99], s[98:99], 11
	v_lshl_add_u64 v[170:171], v[110:111], 0, s[98:99]
	global_load_dwordx4 v[144:147], v[170:171], off
	global_load_dwordx4 v[148:151], v[170:171], off offset:1024
	s_add_i32 s98, s56, 2
	s_ashr_i32 s99, s98, 11
	s_mulk_i32 s99, 0x900
	s_and_b32 s100, s98, 0x7ff
	s_add_i32 s99, s99, s100
	s_addk_i32 s99, 0x100
	s_and_b64 s[100:101], s[2:3], exec
	s_cselect_b32 s98, s99, s98
	s_ashr_i32 s99, s98, 31
	s_lshl_b64 s[98:99], s[98:99], 11
	v_lshl_add_u64 v[172:173], v[110:111], 0, s[98:99]
	global_load_dwordx4 v[152:155], v[172:173], off
	global_load_dwordx4 v[156:159], v[172:173], off offset:1024
	s_add_i32 s98, s56, 3
	s_ashr_i32 s99, s98, 11
	s_mulk_i32 s99, 0x900
	s_and_b32 s100, s98, 0x7ff
	s_add_i32 s99, s99, s100
	s_addk_i32 s99, 0x100
	s_and_b64 s[100:101], s[2:3], exec
	s_cselect_b32 s98, s99, s98
	s_ashr_i32 s99, s98, 31
	s_lshl_b64 s[98:99], s[98:99], 11
	v_lshl_add_u64 v[174:175], v[110:111], 0, s[98:99]
	global_load_dwordx4 v[160:163], v[174:175], off
	global_load_dwordx4 v[164:167], v[174:175], off offset:1024
	s_waitcnt vmcnt(0)
	s_branch .LBB0_38
	s_nop 0
	s_nop 0
	s_nop 0
	s_nop 0
	s_nop 0
	s_nop 0
	s_nop 0
	s_nop 0
	s_nop 0
	s_nop 0
	s_nop 0
	s_nop 0
	s_nop 0
	s_nop 0
	s_nop 0
	s_nop 0
	s_nop 0
	s_nop 0
	s_nop 0
	s_nop 0
	s_nop 0
	s_nop 0
	s_nop 0
	s_nop 0
	s_nop 0
	s_nop 0
	s_nop 0
	s_nop 0
	s_nop 0
	s_nop 0
	s_nop 0
	s_nop 0
	s_nop 0
	s_nop 0
	s_nop 0
	s_nop 0

.LBB0_42:
	s_ashr_i32 s53, s52, 31
	s_lshl_b64 s[50:51], s[52:53], 11
	v_lshl_add_u64 v[64:65], v[110:111], 0, s[50:51]
	v_mov_b32_e32 v68, v136
	v_mov_b32_e32 v69, v137
	v_mov_b32_e32 v70, v138
	v_mov_b32_e32 v71, v139
	s_nop 0
	v_mov_b32_e32 v64, v140
	v_mov_b32_e32 v65, v141
	v_mov_b32_e32 v66, v142
	v_mov_b32_e32 v67, v143
	s_add_i32 s18, s56, 1
	s_and_b64 vcc, exec, s[4:5]
	s_mov_b64 s[14:15], -1
	s_cbranch_vccnz .LBB0_44
	s_ashr_i32 s34, s18, 11
	s_and_b32 s14, s18, 0x7ff
	s_add_i32 s36, s14, 0x100
	s_mul_i32 s14, s34, 0x900
	s_add_i32 s42, s14, s36
	s_mov_b64 s[14:15], 0

.LBB0_46:
	s_ashr_i32 s43, s42, 31
	s_lshl_b64 s[40:41], s[42:43], 11
	v_lshl_add_u64 v[72:73], v[110:111], 0, s[40:41]
	v_mov_b32_e32 v84, v144
	v_mov_b32_e32 v85, v145
	v_mov_b32_e32 v86, v146
	v_mov_b32_e32 v87, v147
	v_mov_b32_e32 v80, v148
	v_mov_b32_e32 v81, v149
	v_mov_b32_e32 v82, v150
	v_mov_b32_e32 v83, v151
	s_add_i32 s18, s56, 2
	s_and_b64 vcc, exec, s[4:5]
	s_mov_b64 s[14:15], -1
	s_cbranch_vccnz .LBB0_48
	s_ashr_i32 s24, s18, 11
	s_and_b32 s14, s18, 0x7ff
	s_add_i32 s26, s14, 0x100
	s_mul_i32 s14, s24, 0x900
	s_add_i32 s30, s14, s26
	s_mov_b64 s[14:15], 0

.LBB0_50:
	s_ashr_i32 s31, s30, 31
	s_lshl_b64 s[28:29], s[30:31], 11
	v_lshl_add_u64 v[72:73], v[110:111], 0, s[28:29]
	v_mov_b32_e32 v76, v152
	v_mov_b32_e32 v77, v153
	v_mov_b32_e32 v78, v154
	v_mov_b32_e32 v79, v155
	s_nop 0
	v_mov_b32_e32 v72, v156
	v_mov_b32_e32 v73, v157
	v_mov_b32_e32 v74, v158
	v_mov_b32_e32 v75, v159
	s_add_i32 s15, s56, 3
	s_and_b64 vcc, exec, s[4:5]
	s_mov_b64 s[4:5], -1
	s_cbranch_vccnz .LBB0_52
	s_ashr_i32 s14, s15, 11
	s_and_b32 s4, s15, 0x7ff
	s_add_i32 s18, s4, 0x100
	s_mul_i32 s4, s14, 0x900
	s_add_i32 s22, s4, s18
	s_mov_b64 s[4:5], 0

.LBB0_54:
	s_nop 0
	v_lshlrev_b32_e32 v88, 16, v68
	v_and_b32_e32 v89, 0xffff0000, v68
	v_add_f32_e32 v68, 0, v88
	v_add_f32_e32 v68, v68, v89
	v_lshlrev_b32_e32 v90, 16, v69
	v_and_b32_e32 v91, 0xffff0000, v69
	v_add_f32_e32 v68, v68, v90
	v_add_f32_e32 v68, v68, v91
	v_lshlrev_b32_e32 v92, 16, v70
	v_and_b32_e32 v93, 0xffff0000, v70
	v_add_f32_e32 v68, v68, v92
	v_add_f32_e32 v68, v68, v93
	v_lshlrev_b32_e32 v94, 16, v71
	v_and_b32_e32 v95, 0xffff0000, v71
	v_add_f32_e32 v68, v68, v94
	v_add_f32_e32 v68, v68, v95
	s_nop 0
	v_lshlrev_b32_e32 v98, 16, v64
	v_and_b32_e32 v99, 0xffff0000, v64
	v_add_f32_e32 v64, v68, v98
	v_add_f32_e32 v64, v64, v99
	v_lshlrev_b32_e32 v100, 16, v65
	v_and_b32_e32 v101, 0xffff0000, v65
	v_add_f32_e32 v64, v64, v100
	v_add_f32_e32 v64, v64, v101
	v_lshlrev_b32_e32 v102, 16, v66
	v_and_b32_e32 v103, 0xffff0000, v66
	v_add_f32_e32 v64, v64, v102
	v_add_f32_e32 v64, v64, v103
	v_lshlrev_b32_e32 v118, 16, v67
	v_and_b32_e32 v119, 0xffff0000, v67
	v_add_f32_e32 v64, v64, v118
	v_add_f32_e32 v64, v64, v119
	s_ashr_i32 s23, s22, 31
	s_lshl_b64 s[20:21], s[22:23], 11
	s_nop 1
	v_add_f32_dpp v64, v64, v64 quad_perm:[1,0,3,2] row_mask:0xf bank_mask:0xf
	s_nop 1
	v_add_f32_dpp v64, v64, v64 quad_perm:[2,3,0,1] row_mask:0xf bank_mask:0xf
	s_nop 1
	v_add_f32_dpp v64, v64, v64 row_half_mirror row_mask:0xf bank_mask:0xf
	s_nop 1
	v_add_f32_dpp v64, v64, v64 row_mirror row_mask:0xf bank_mask:0xf
	v_mov_b32_e32 v65, v64
	v_mov_b32_e32 v96, v64
	s_nop 1
	v_permlane16_swap_b32_e32 v65, v96
	v_add_f32_e32 v96, v96, v65
	v_lshl_add_u64 v[64:65], v[110:111], 0, s[20:21]
	v_mov_b32_e32 v68, v160
	v_mov_b32_e32 v69, v161
	v_mov_b32_e32 v70, v162
	v_mov_b32_e32 v71, v163
	s_nop 0
	v_mov_b32_e32 v64, v164
	v_mov_b32_e32 v65, v165
	v_mov_b32_e32 v66, v166
	v_mov_b32_e32 v67, v167
	s_add_i32 s98, s56, 4
	s_cmp_ge_i32 s98, s57
	s_cbranch_scc1 .Lln_no_pf
	s_add_i32 s98, s56, 4
	s_ashr_i32 s99, s98, 11
	s_mulk_i32 s99, 0x900
	s_and_b32 s100, s98, 0x7ff
	s_add_i32 s99, s99, s100
	s_addk_i32 s99, 0x100
	s_and_b64 s[100:101], s[2:3], exec
	s_cselect_b32 s98, s99, s98
	s_ashr_i32 s99, s98, 31
	s_lshl_b64 s[98:99], s[98:99], 11
	v_lshl_add_u64 v[168:169], v[110:111], 0, s[98:99]
	global_load_dwordx4 v[136:139], v[168:169], off
	global_load_dwordx4 v[140:143], v[168:169], off offset:1024
	s_add_i32 s98, s56, 5
	s_ashr_i32 s99, s98, 11
	s_mulk_i32 s99, 0x900
	s_and_b32 s100, s98, 0x7ff
	s_add_i32 s99, s99, s100
	s_addk_i32 s99, 0x100
	s_and_b64 s[100:101], s[2:3], exec
	s_cselect_b32 s98, s99, s98
	s_ashr_i32 s99, s98, 31
	s_lshl_b64 s[98:99], s[98:99], 11
	v_lshl_add_u64 v[170:171], v[110:111], 0, s[98:99]
	global_load_dwordx4 v[144:147], v[170:171], off
	global_load_dwordx4 v[148:151], v[170:171], off offset:1024
	s_add_i32 s98, s56, 6
	s_ashr_i32 s99, s98, 11
	s_mulk_i32 s99, 0x900
	s_and_b32 s100, s98, 0x7ff
	s_add_i32 s99, s99, s100
	s_addk_i32 s99, 0x100
	s_and_b64 s[100:101], s[2:3], exec
	s_cselect_b32 s98, s99, s98
	s_ashr_i32 s99, s98, 31
	s_lshl_b64 s[98:99], s[98:99], 11
	v_lshl_add_u64 v[172:173], v[110:111], 0, s[98:99]
	global_load_dwordx4 v[152:155], v[172:173], off
	global_load_dwordx4 v[156:159], v[172:173], off offset:1024
	s_add_i32 s98, s56, 7
	s_ashr_i32 s99, s98, 11
	s_mulk_i32 s99, 0x900
	s_and_b32 s100, s98, 0x7ff
	s_add_i32 s99, s99, s100
	s_addk_i32 s99, 0x100
	s_and_b64 s[100:101], s[2:3], exec
	s_cselect_b32 s98, s99, s98
	s_ashr_i32 s99, s98, 31
	s_lshl_b64 s[98:99], s[98:99], 11
	v_lshl_add_u64 v[174:175], v[110:111], 0, s[98:99]
	global_load_dwordx4 v[160:163], v[174:175], off
	global_load_dwordx4 v[164:167], v[174:175], off offset:1024
.Lln_no_pf:
	v_mov_b32_e32 v97, v96
	s_nop 1
	v_permlane32_swap_b32_e32 v97, v96
	v_add_f32_e32 v96, v96, v97
	v_mul_f32_e32 v96, 0x3a800000, v96
	v_pk_add_f32 v[88:89], v[88:89], v[96:97] op_sel_hi:[1,0] neg_lo:[0,1] neg_hi:[0,1]
	v_pk_add_f32 v[90:91], v[90:91], v[96:97] op_sel_hi:[1,0] neg_lo:[0,1] neg_hi:[0,1]
	v_pk_mul_f32 v[126:127], v[88:89], v[88:89]
	v_pk_add_f32 v[92:93], v[92:93], v[96:97] op_sel_hi:[1,0] neg_lo:[0,1] neg_hi:[0,1]
	v_pk_mul_f32 v[128:129], v[90:91], v[90:91]
	v_pk_add_f32 v[94:95], v[94:95], v[96:97] op_sel_hi:[1,0] neg_lo:[0,1] neg_hi:[0,1]
	v_pk_add_f32 v[104:105], v[98:99], v[96:97] op_sel_hi:[1,0] neg_lo:[0,1] neg_hi:[0,1]
	v_pk_add_f32 v[106:107], v[100:101], v[96:97] op_sel_hi:[1,0] neg_lo:[0,1] neg_hi:[0,1]
	v_pk_add_f32 v[116:117], v[102:103], v[96:97] op_sel_hi:[1,0] neg_lo:[0,1] neg_hi:[0,1]
	v_pk_add_f32 v[118:119], v[118:119], v[96:97] op_sel_hi:[1,0] neg_lo:[0,1] neg_hi:[0,1]
	v_add_f32_e32 v97, v126, v127
	v_add_f32_e32 v97, v128, v97
	v_pk_mul_f32 v[130:131], v[92:93], v[92:93]
	v_add_f32_e32 v97, v129, v97
	v_add_f32_e32 v97, v130, v97
	v_pk_mul_f32 v[132:133], v[94:95], v[94:95]
	v_add_f32_e32 v97, v131, v97
	v_add_f32_e32 v97, v132, v97
	v_pk_mul_f32 v[98:99], v[104:105], v[104:105]
	v_add_f32_e32 v97, v133, v97
	v_add_f32_e32 v97, v98, v97
	v_pk_mul_f32 v[100:101], v[106:107], v[106:107]
	v_add_f32_e32 v97, v99, v97
	v_add_f32_e32 v97, v100, v97
	v_pk_mul_f32 v[102:103], v[116:117], v[116:117]
	v_add_f32_e32 v97, v101, v97
	v_add_f32_e32 v97, v102, v97
	v_pk_mul_f32 v[134:135], v[118:119], v[118:119]
	v_add_f32_e32 v97, v103, v97
	v_add_f32_e32 v97, v134, v97
	v_add_f32_e32 v97, v135, v97
	s_nop 1
	v_add_f32_dpp v97, v97, v97 quad_perm:[1,0,3,2] row_mask:0xf bank_mask:0xf
	s_nop 1
	v_add_f32_dpp v97, v97, v97 quad_perm:[2,3,0,1] row_mask:0xf bank_mask:0xf
	s_nop 1
	v_add_f32_dpp v97, v97, v97 row_half_mirror row_mask:0xf bank_mask:0xf
	s_nop 1
	v_add_f32_dpp v97, v97, v97 row_mirror row_mask:0xf bank_mask:0xf
	v_mov_b32_e32 v98, v97
	s_nop 1
	v_permlane16_swap_b32_e32 v98, v97
	v_add_f32_e32 v97, v97, v98
	v_mov_b32_e32 v98, v97
	s_nop 1
	v_permlane32_swap_b32_e32 v98, v97
	v_add_f32_e32 v97, v97, v98
	v_fmamk_f32 v97, v97, 0x3a800000, v225
	v_mul_f32_e32 v98, 0x4b800000, v97
	v_cmp_gt_f32_e32 vcc, s54, v97
	s_nop 1
	v_cndmask_b32_e32 v97, v97, v98, vcc
	v_rsq_f32_e32 v97, v97
	s_nop 0
	v_mul_f32_e32 v98, 0x45800000, v97
	v_cndmask_b32_e32 v120, v97, v98, vcc
	s_and_saveexec_b64 s[4:5], s[12:13]
	s_cbranch_execz .LBB0_56
	s_lshl_b64 s[52:53], s[52:53], 3
	s_add_u32 s52, s64, s52
	v_mov_b32_e32 v97, v120
	s_addc_u32 s53, s65, s53
	global_store_dwordx2 v193, v[96:97], s[52:53]

.LBB0_63:
	v_cndmask_b32_e64 v96, 0, 1, s[6:7]
	v_cmp_ne_u32_e64 s[4:5], 1, v96
	s_andn2_b64 vcc, exec, s[6:7]
	s_cbranch_vccnz .LBB0_66
	s_cmpk_gt_i32 s48, 0xff
	s_cselect_b32 s15, s46, 32
	s_cmp_eq_u32 s15, s68
	s_cbranch_scc1 .LBB0_66
	v_mad_i64_i32 v[40:41], s[52:53], s15, v252, v[112:113]
	s_lshl_b32 s52, s61, 2
	s_mov_b32 s53, s45
	v_lshl_add_u64 v[52:53], v[40:41], 0, s[52:53]
	s_lshl_b32 s52, s60, 2
	v_lshl_add_u64 v[60:61], v[40:41], 0, s[52:53]
	global_load_dwordx4 v[32:35], v[52:53], off
	global_load_dwordx4 v[36:39], v[52:53], off offset:16
	global_load_dwordx4 v[40:43], v[60:61], off
	global_load_dwordx4 v[44:47], v[60:61], off offset:16
	global_load_dwordx4 v[48:51], v[52:53], off offset:2048
	s_nop 0
	global_load_dwordx4 v[52:55], v[52:53], off offset:2064
	s_nop 0
	global_load_dwordx4 v[56:59], v[60:61], off offset:2048
	s_nop 0
	global_load_dwordx4 v[60:63], v[60:61], off offset:2064
	s_waitcnt vmcnt(0)
	s_mov_b32 s68, s15
.LBB0_66:
	v_pk_mul_f32 v[88:89], v[88:89], v[120:121] op_sel_hi:[1,0]
	s_mov_b64 s[52:53], -1
	v_pk_fma_f32 v[100:101], v[4:5], v[88:89], v[12:13]
	v_pk_mul_f32 v[88:89], v[90:91], v[120:121] op_sel_hi:[1,0]
	v_pk_mul_f32 v[90:91], v[118:119], v[120:121] op_sel_hi:[1,0]
	v_pk_fma_f32 v[102:103], v[6:7], v[88:89], v[14:15]
	v_pk_mul_f32 v[88:89], v[92:93], v[120:121] op_sel_hi:[1,0]
	v_pk_fma_f32 v[90:91], v[18:19], v[90:91], v[26:27]
	v_pk_fma_f32 v[96:97], v[0:1], v[88:89], v[8:9]
	v_pk_mul_f32 v[88:89], v[94:95], v[120:121] op_sel_hi:[1,0]
	s_and_b64 vcc, exec, s[6:7]
	v_pk_fma_f32 v[98:99], v[2:3], v[88:89], v[10:11]
	v_pk_mul_f32 v[88:89], v[104:105], v[120:121] op_sel_hi:[1,0]
	s_nop 0
	v_pk_fma_f32 v[92:93], v[20:21], v[88:89], v[28:29]
	v_pk_mul_f32 v[88:89], v[106:107], v[120:121] op_sel_hi:[1,0]
	s_nop 0
	v_pk_fma_f32 v[94:95], v[22:23], v[88:89], v[30:31]
	v_pk_mul_f32 v[88:89], v[116:117], v[120:121] op_sel_hi:[1,0]
	s_nop 0
	v_pk_fma_f32 v[88:89], v[16:17], v[88:89], v[24:25]
	s_cbranch_vccz .LBB0_72
	s_cmp_gt_i32 s44, -1
	s_cselect_b64 s[54:55], -1, 0
	s_lshl_b64 s[52:53], s[44:45], 11
	s_nop 0
	v_pk_add_f32 v[104:105], v[40:41], 1.0 op_sel_hi:[1,0]
	v_pk_add_f32 v[106:107], v[42:43], 1.0 op_sel_hi:[1,0]
	s_nop 0
	v_pk_add_f32 v[116:117], v[44:45], 1.0 op_sel_hi:[1,0]
	v_pk_add_f32 v[118:119], v[46:47], 1.0 op_sel_hi:[1,0]
	s_add_u32 s52, s62, s52
	v_pk_fma_f32 v[104:105], v[100:101], v[104:105], v[32:33]
	v_pk_fma_f32 v[106:107], v[102:103], v[106:107], v[34:35]
	v_pk_fma_f32 v[116:117], v[96:97], v[116:117], v[36:37]
	v_pk_fma_f32 v[118:119], v[98:99], v[118:119], v[38:39]
	s_addc_u32 s53, s63, s53
	s_cmp_lt_i32 s44, 0
	v_cvt_pk_bf16_f32 v104, v104, v105
	v_cvt_pk_bf16_f32 v105, v106, v107
	v_cvt_pk_bf16_f32 v106, v116, v117
	v_cvt_pk_bf16_f32 v107, v118, v119
	v_lshl_add_u64 v[116:117], v[114:115], 0, s[50:51]
	global_store_dwordx4 v[116:117], v[104:107], off
	s_cbranch_scc1 .LBB0_69
	v_lshlrev_b32_e32 v118, 1, v108
	global_store_dwordx4 v118, v[104:107], s[52:53]
.LBB0_69:
	s_nop 0
	s_nop 0
	v_pk_add_f32 v[104:105], v[56:57], 1.0 op_sel_hi:[1,0]
	v_pk_add_f32 v[106:107], v[58:59], 1.0 op_sel_hi:[1,0]
	s_nop 0
	v_pk_add_f32 v[118:119], v[60:61], 1.0 op_sel_hi:[1,0]
	v_pk_add_f32 v[126:127], v[62:63], 1.0 op_sel_hi:[1,0]
	v_pk_fma_f32 v[104:105], v[92:93], v[104:105], v[48:49]
	v_pk_fma_f32 v[106:107], v[94:95], v[106:107], v[50:51]
	v_pk_fma_f32 v[118:119], v[88:89], v[118:119], v[52:53]
	v_pk_fma_f32 v[126:127], v[90:91], v[126:127], v[54:55]
	v_cvt_pk_bf16_f32 v104, v104, v105
	v_cvt_pk_bf16_f32 v105, v106, v107
	v_cvt_pk_bf16_f32 v106, v118, v119
	v_cvt_pk_bf16_f32 v107, v126, v127
	s_andn2_b64 vcc, exec, s[54:55]
	global_store_dwordx4 v[116:117], v[104:107], off offset:1024
	s_cbranch_vccnz .LBB0_71
	v_lshlrev_b32_e32 v116, 1, v108
	global_store_dwordx4 v116, v[104:107], s[52:53] offset:1024

.LBB0_74:
	s_nop 0
	s_nop 0
	v_lshlrev_b32_e32 v90, 16, v84
	v_and_b32_e32 v91, 0xffff0000, v84
	v_add_f32_e32 v84, 0, v90
	v_add_f32_e32 v88, v84, v91
	v_lshlrev_b32_e32 v84, 16, v85
	v_and_b32_e32 v85, 0xffff0000, v85
	v_add_f32_e32 v88, v88, v84
	v_add_f32_e32 v88, v88, v85
	v_lshlrev_b32_e32 v92, 16, v86
	v_and_b32_e32 v93, 0xffff0000, v86
	v_add_f32_e32 v86, v88, v92
	v_add_f32_e32 v88, v86, v93
	v_lshlrev_b32_e32 v86, 16, v87
	v_and_b32_e32 v87, 0xffff0000, v87
	v_add_f32_e32 v88, v88, v86
	v_add_f32_e32 v88, v88, v87
	s_nop 0
	v_lshlrev_b32_e32 v94, 16, v80
	v_and_b32_e32 v95, 0xffff0000, v80
	v_add_f32_e32 v80, v88, v94
	v_add_f32_e32 v80, v80, v95
	v_lshlrev_b32_e32 v98, 16, v81
	v_and_b32_e32 v99, 0xffff0000, v81
	v_add_f32_e32 v80, v80, v98
	v_add_f32_e32 v80, v80, v99
	v_lshlrev_b32_e32 v100, 16, v82
	v_and_b32_e32 v101, 0xffff0000, v82
	v_add_f32_e32 v80, v80, v100
	v_add_f32_e32 v80, v80, v101
	v_lshlrev_b32_e32 v102, 16, v83
	v_and_b32_e32 v103, 0xffff0000, v83
	v_add_f32_e32 v80, v80, v102
	v_add_f32_e32 v80, v80, v103
	s_nop 1
	v_add_f32_dpp v80, v80, v80 quad_perm:[1,0,3,2] row_mask:0xf bank_mask:0xf
	s_nop 1
	v_add_f32_dpp v80, v80, v80 quad_perm:[2,3,0,1] row_mask:0xf bank_mask:0xf
	s_nop 1
	v_add_f32_dpp v80, v80, v80 row_half_mirror row_mask:0xf bank_mask:0xf
	s_nop 1
	v_add_f32_dpp v80, v80, v80 row_mirror row_mask:0xf bank_mask:0xf
	v_mov_b32_e32 v81, v80
	s_nop 1
	v_permlane16_swap_b32_e32 v81, v80
	v_add_f32_e32 v80, v80, v81
	v_mov_b32_e32 v81, v80
	s_nop 1
	v_permlane32_swap_b32_e32 v81, v80
	v_add_f32_e32 v80, v80, v81
	v_mul_f32_e32 v88, 0x3a800000, v80
	v_pk_add_f32 v[80:81], v[90:91], v[88:89] op_sel_hi:[1,0] neg_lo:[0,1] neg_hi:[0,1]
	v_pk_add_f32 v[82:83], v[84:85], v[88:89] op_sel_hi:[1,0] neg_lo:[0,1] neg_hi:[0,1]
	v_pk_mul_f32 v[90:91], v[80:81], v[80:81]
	v_pk_add_f32 v[84:85], v[92:93], v[88:89] op_sel_hi:[1,0] neg_lo:[0,1] neg_hi:[0,1]
	v_pk_add_f32 v[86:87], v[86:87], v[88:89] op_sel_hi:[1,0] neg_lo:[0,1] neg_hi:[0,1]
	v_pk_add_f32 v[96:97], v[94:95], v[88:89] op_sel_hi:[1,0] neg_lo:[0,1] neg_hi:[0,1]
	v_pk_add_f32 v[98:99], v[98:99], v[88:89] op_sel_hi:[1,0] neg_lo:[0,1] neg_hi:[0,1]
	v_pk_mul_f32 v[92:93], v[82:83], v[82:83]
	v_pk_add_f32 v[100:101], v[100:101], v[88:89] op_sel_hi:[1,0] neg_lo:[0,1] neg_hi:[0,1]
	v_pk_add_f32 v[102:103], v[102:103], v[88:89] op_sel_hi:[1,0] neg_lo:[0,1] neg_hi:[0,1]
	v_add_f32_e32 v89, v90, v91
	v_add_f32_e32 v89, v92, v89
	v_pk_mul_f32 v[94:95], v[84:85], v[84:85]
	v_add_f32_e32 v89, v93, v89
	v_add_f32_e32 v89, v94, v89
	v_pk_mul_f32 v[104:105], v[86:87], v[86:87]
	v_add_f32_e32 v89, v95, v89
	v_add_f32_e32 v89, v104, v89
	v_pk_mul_f32 v[106:107], v[96:97], v[96:97]
	v_add_f32_e32 v89, v105, v89
	v_add_f32_e32 v89, v106, v89
	v_pk_mul_f32 v[116:117], v[98:99], v[98:99]
	v_add_f32_e32 v89, v107, v89
	v_add_f32_e32 v89, v116, v89
	v_pk_mul_f32 v[118:119], v[100:101], v[100:101]
	v_add_f32_e32 v89, v117, v89
	v_add_f32_e32 v89, v118, v89
	v_pk_mul_f32 v[126:127], v[102:103], v[102:103]
	v_add_f32_e32 v89, v119, v89
	v_add_f32_e32 v89, v126, v89
	v_add_f32_e32 v89, v127, v89
	s_nop 1
	v_add_f32_dpp v89, v89, v89 quad_perm:[1,0,3,2] row_mask:0xf bank_mask:0xf
	s_nop 1
	v_add_f32_dpp v89, v89, v89 quad_perm:[2,3,0,1] row_mask:0xf bank_mask:0xf
	s_nop 1
	v_add_f32_dpp v89, v89, v89 row_half_mirror row_mask:0xf bank_mask:0xf
	s_nop 1
	v_add_f32_dpp v89, v89, v89 row_mirror row_mask:0xf bank_mask:0xf
	v_mov_b32_e32 v90, v89
	s_nop 1
	v_permlane16_swap_b32_e32 v90, v89
	v_add_f32_e32 v89, v89, v90
	v_mov_b32_e32 v90, v89
	s_nop 1
	v_permlane32_swap_b32_e32 v90, v89
	v_add_f32_e32 v89, v89, v90
	v_fmamk_f32 v89, v89, 0x3a800000, v225
	v_mul_f32_e32 v90, 0x4b800000, v89
	v_cmp_gt_f32_e32 vcc, s54, v89
	s_nop 1
	v_cndmask_b32_e32 v89, v89, v90, vcc
	v_rsq_f32_e32 v89, v89
	s_nop 0
	v_mul_f32_e32 v90, 0x45800000, v89
	v_cndmask_b32_e32 v104, v89, v90, vcc
	s_and_saveexec_b64 s[46:47], s[12:13]
	s_cbranch_execz .LBB0_76
	s_lshl_b64 s[42:43], s[42:43], 3
	s_add_u32 s42, s64, s42
	v_mov_b32_e32 v89, v104
	s_addc_u32 s43, s65, s43
	global_store_dwordx2 v193, v[88:89], s[42:43]

.LBB0_83:
	s_and_b64 vcc, exec, s[4:5]
	s_cbranch_vccnz .LBB0_86
	s_cmpk_gt_i32 s36, 0xff
	s_cselect_b32 s15, s34, 32
	s_cmp_eq_u32 s15, s68
	s_cbranch_scc1 .LBB0_86
	v_mad_i64_i32 v[40:41], s[42:43], s15, v252, v[112:113]
	s_lshl_b32 s42, s61, 2
	s_mov_b32 s43, s45
	s_nop 0
	v_lshl_add_u64 v[52:53], v[40:41], 0, s[42:43]
	s_lshl_b32 s42, s60, 2
	s_waitcnt vmcnt(0)
	v_lshl_add_u64 v[60:61], v[40:41], 0, s[42:43]
	global_load_dwordx4 v[32:35], v[52:53], off
	global_load_dwordx4 v[36:39], v[52:53], off offset:16
	global_load_dwordx4 v[40:43], v[60:61], off
	global_load_dwordx4 v[44:47], v[60:61], off offset:16
	global_load_dwordx4 v[48:51], v[52:53], off offset:2048
	s_nop 0
	global_load_dwordx4 v[52:55], v[52:53], off offset:2064
	s_nop 0
	global_load_dwordx4 v[56:59], v[60:61], off offset:2048
	s_nop 0
	global_load_dwordx4 v[60:63], v[60:61], off offset:2064
	s_waitcnt vmcnt(0)
	s_mov_b32 s68, s15
.LBB0_86:
	v_pk_mul_f32 v[80:81], v[80:81], v[104:105] op_sel_hi:[1,0]
	s_mov_b64 s[42:43], -1
	v_pk_fma_f32 v[92:93], v[4:5], v[80:81], v[12:13]
	v_pk_mul_f32 v[80:81], v[82:83], v[104:105] op_sel_hi:[1,0]
	v_pk_mul_f32 v[82:83], v[102:103], v[104:105] op_sel_hi:[1,0]
	v_pk_fma_f32 v[94:95], v[6:7], v[80:81], v[14:15]
	v_pk_mul_f32 v[80:81], v[84:85], v[104:105] op_sel_hi:[1,0]
	v_pk_fma_f32 v[82:83], v[18:19], v[82:83], v[26:27]
	v_pk_fma_f32 v[88:89], v[0:1], v[80:81], v[8:9]
	v_pk_mul_f32 v[80:81], v[86:87], v[104:105] op_sel_hi:[1,0]
	s_and_b64 vcc, exec, s[6:7]
	v_pk_fma_f32 v[90:91], v[2:3], v[80:81], v[10:11]
	v_pk_mul_f32 v[80:81], v[96:97], v[104:105] op_sel_hi:[1,0]
	s_nop 0
	v_pk_fma_f32 v[84:85], v[20:21], v[80:81], v[28:29]
	v_pk_mul_f32 v[80:81], v[98:99], v[104:105] op_sel_hi:[1,0]
	s_nop 0
	v_pk_fma_f32 v[86:87], v[22:23], v[80:81], v[30:31]
	v_pk_mul_f32 v[80:81], v[100:101], v[104:105] op_sel_hi:[1,0]
	s_nop 0
	v_pk_fma_f32 v[80:81], v[16:17], v[80:81], v[24:25]
	s_cbranch_vccz .LBB0_92
	s_cmp_gt_i32 s44, -1
	s_cselect_b64 s[46:47], -1, 0
	s_lshl_b64 s[42:43], s[44:45], 11
	s_nop 0
	v_pk_add_f32 v[96:97], v[40:41], 1.0 op_sel_hi:[1,0]
	v_pk_add_f32 v[98:99], v[42:43], 1.0 op_sel_hi:[1,0]
	s_nop 0
	v_pk_add_f32 v[100:101], v[44:45], 1.0 op_sel_hi:[1,0]
	v_pk_add_f32 v[102:103], v[46:47], 1.0 op_sel_hi:[1,0]
	s_add_u32 s42, s62, s42
	v_pk_fma_f32 v[96:97], v[92:93], v[96:97], v[32:33]
	v_pk_fma_f32 v[98:99], v[94:95], v[98:99], v[34:35]
	v_pk_fma_f32 v[100:101], v[88:89], v[100:101], v[36:37]
	v_pk_fma_f32 v[102:103], v[90:91], v[102:103], v[38:39]
	s_addc_u32 s43, s63, s43
	s_cmp_lt_i32 s44, 0
	v_cvt_pk_bf16_f32 v96, v96, v97
	v_cvt_pk_bf16_f32 v97, v98, v99
	v_cvt_pk_bf16_f32 v98, v100, v101
	v_cvt_pk_bf16_f32 v99, v102, v103
	v_lshl_add_u64 v[100:101], v[114:115], 0, s[40:41]
	global_store_dwordx4 v[100:101], v[96:99], off
	s_cbranch_scc1 .LBB0_89
	v_lshlrev_b32_e32 v102, 1, v108
	global_store_dwordx4 v102, v[96:99], s[42:43]
.LBB0_89:
	s_nop 0
	s_nop 0
	v_pk_add_f32 v[96:97], v[56:57], 1.0 op_sel_hi:[1,0]
	v_pk_add_f32 v[98:99], v[58:59], 1.0 op_sel_hi:[1,0]
	s_nop 0
	v_pk_add_f32 v[102:103], v[60:61], 1.0 op_sel_hi:[1,0]
	v_pk_add_f32 v[104:105], v[62:63], 1.0 op_sel_hi:[1,0]
	v_pk_fma_f32 v[96:97], v[84:85], v[96:97], v[48:49]
	v_pk_fma_f32 v[98:99], v[86:87], v[98:99], v[50:51]
	v_pk_fma_f32 v[102:103], v[80:81], v[102:103], v[52:53]
	v_pk_fma_f32 v[104:105], v[82:83], v[104:105], v[54:55]
	v_cvt_pk_bf16_f32 v96, v96, v97
	v_cvt_pk_bf16_f32 v97, v98, v99
	v_cvt_pk_bf16_f32 v98, v102, v103
	v_cvt_pk_bf16_f32 v99, v104, v105
	s_andn2_b64 vcc, exec, s[46:47]
	global_store_dwordx4 v[100:101], v[96:99], off offset:1024
	s_cbranch_vccnz .LBB0_91
	v_lshlrev_b32_e32 v100, 1, v108
	global_store_dwordx4 v100, v[96:99], s[42:43] offset:1024

.LBB0_94:
	s_nop 0
	s_nop 0
	v_lshlrev_b32_e32 v82, 16, v76
	v_and_b32_e32 v83, 0xffff0000, v76
	v_add_f32_e32 v76, 0, v82
	v_add_f32_e32 v80, v76, v83
	v_lshlrev_b32_e32 v76, 16, v77
	v_and_b32_e32 v77, 0xffff0000, v77
	v_add_f32_e32 v80, v80, v76
	v_add_f32_e32 v80, v80, v77
	v_lshlrev_b32_e32 v84, 16, v78
	v_and_b32_e32 v85, 0xffff0000, v78
	v_add_f32_e32 v78, v80, v84
	v_add_f32_e32 v80, v78, v85
	v_lshlrev_b32_e32 v78, 16, v79
	v_and_b32_e32 v79, 0xffff0000, v79
	v_add_f32_e32 v80, v80, v78
	v_add_f32_e32 v80, v80, v79
	s_nop 0
	v_lshlrev_b32_e32 v86, 16, v72
	v_and_b32_e32 v87, 0xffff0000, v72
	v_add_f32_e32 v72, v80, v86
	v_add_f32_e32 v72, v72, v87
	v_lshlrev_b32_e32 v90, 16, v73
	v_and_b32_e32 v91, 0xffff0000, v73
	v_add_f32_e32 v72, v72, v90
	v_add_f32_e32 v72, v72, v91
	v_lshlrev_b32_e32 v92, 16, v74
	v_and_b32_e32 v93, 0xffff0000, v74
	v_add_f32_e32 v72, v72, v92
	v_add_f32_e32 v72, v72, v93
	v_lshlrev_b32_e32 v94, 16, v75
	v_and_b32_e32 v95, 0xffff0000, v75
	v_add_f32_e32 v72, v72, v94
	v_add_f32_e32 v72, v72, v95
	s_nop 1
	v_add_f32_dpp v72, v72, v72 quad_perm:[1,0,3,2] row_mask:0xf bank_mask:0xf
	s_nop 1
	v_add_f32_dpp v72, v72, v72 quad_perm:[2,3,0,1] row_mask:0xf bank_mask:0xf
	s_nop 1
	v_add_f32_dpp v72, v72, v72 row_half_mirror row_mask:0xf bank_mask:0xf
	s_nop 1
	v_add_f32_dpp v72, v72, v72 row_mirror row_mask:0xf bank_mask:0xf
	v_mov_b32_e32 v73, v72
	s_nop 1
	v_permlane16_swap_b32_e32 v73, v72
	v_add_f32_e32 v72, v72, v73
	v_mov_b32_e32 v73, v72
	s_nop 1
	v_permlane32_swap_b32_e32 v73, v72
	v_add_f32_e32 v72, v72, v73
	v_mul_f32_e32 v80, 0x3a800000, v72
	v_pk_add_f32 v[72:73], v[82:83], v[80:81] op_sel_hi:[1,0] neg_lo:[0,1] neg_hi:[0,1]
	v_pk_add_f32 v[74:75], v[76:77], v[80:81] op_sel_hi:[1,0] neg_lo:[0,1] neg_hi:[0,1]
	v_pk_mul_f32 v[82:83], v[72:73], v[72:73]
	v_pk_add_f32 v[76:77], v[84:85], v[80:81] op_sel_hi:[1,0] neg_lo:[0,1] neg_hi:[0,1]
	v_pk_add_f32 v[78:79], v[78:79], v[80:81] op_sel_hi:[1,0] neg_lo:[0,1] neg_hi:[0,1]
	v_pk_add_f32 v[88:89], v[86:87], v[80:81] op_sel_hi:[1,0] neg_lo:[0,1] neg_hi:[0,1]
	v_pk_add_f32 v[90:91], v[90:91], v[80:81] op_sel_hi:[1,0] neg_lo:[0,1] neg_hi:[0,1]
	v_pk_mul_f32 v[84:85], v[74:75], v[74:75]
	v_pk_add_f32 v[92:93], v[92:93], v[80:81] op_sel_hi:[1,0] neg_lo:[0,1] neg_hi:[0,1]
	v_pk_add_f32 v[94:95], v[94:95], v[80:81] op_sel_hi:[1,0] neg_lo:[0,1] neg_hi:[0,1]
	v_add_f32_e32 v81, v82, v83
	v_add_f32_e32 v81, v84, v81
	v_pk_mul_f32 v[86:87], v[76:77], v[76:77]
	v_add_f32_e32 v81, v85, v81
	v_add_f32_e32 v81, v86, v81
	v_pk_mul_f32 v[96:97], v[78:79], v[78:79]
	v_add_f32_e32 v81, v87, v81
	v_add_f32_e32 v81, v96, v81
	v_pk_mul_f32 v[98:99], v[88:89], v[88:89]
	v_add_f32_e32 v81, v97, v81
	v_add_f32_e32 v81, v98, v81
	v_pk_mul_f32 v[100:101], v[90:91], v[90:91]
	v_add_f32_e32 v81, v99, v81
	v_add_f32_e32 v81, v100, v81
	v_pk_mul_f32 v[102:103], v[92:93], v[92:93]
	v_add_f32_e32 v81, v101, v81
	v_add_f32_e32 v81, v102, v81
	v_pk_mul_f32 v[104:105], v[94:95], v[94:95]
	v_add_f32_e32 v81, v103, v81
	v_add_f32_e32 v81, v104, v81
	v_add_f32_e32 v81, v105, v81
	s_nop 1
	v_add_f32_dpp v81, v81, v81 quad_perm:[1,0,3,2] row_mask:0xf bank_mask:0xf
	s_nop 1
	v_add_f32_dpp v81, v81, v81 quad_perm:[2,3,0,1] row_mask:0xf bank_mask:0xf
	s_nop 1
	v_add_f32_dpp v81, v81, v81 row_half_mirror row_mask:0xf bank_mask:0xf
	s_nop 1
	v_add_f32_dpp v81, v81, v81 row_mirror row_mask:0xf bank_mask:0xf
	v_mov_b32_e32 v82, v81
	s_nop 1
	v_permlane16_swap_b32_e32 v82, v81
	v_add_f32_e32 v81, v81, v82
	v_mov_b32_e32 v82, v81
	s_nop 1
	v_permlane32_swap_b32_e32 v82, v81
	v_add_f32_e32 v81, v81, v82
	v_fmamk_f32 v81, v81, 0x3a800000, v225
	v_mul_f32_e32 v82, 0x4b800000, v81
	v_cmp_gt_f32_e32 vcc, s54, v81
	s_nop 1
	v_cndmask_b32_e32 v81, v81, v82, vcc
	v_rsq_f32_e32 v81, v81
	s_nop 0
	v_mul_f32_e32 v82, 0x45800000, v81
	v_cndmask_b32_e32 v96, v81, v82, vcc
	s_and_saveexec_b64 s[34:35], s[12:13]
	s_cbranch_execz .LBB0_96
	s_lshl_b64 s[30:31], s[30:31], 3
	s_add_u32 s30, s64, s30
	v_mov_b32_e32 v81, v96
	s_addc_u32 s31, s65, s31
	global_store_dwordx2 v193, v[80:81], s[30:31]

.LBB0_103:
	s_and_b64 vcc, exec, s[4:5]
	s_cbranch_vccnz .LBB0_106
	s_cmpk_gt_i32 s26, 0xff
	s_cselect_b32 s15, s24, 32
	s_cmp_eq_u32 s15, s68
	s_cbranch_scc1 .LBB0_106
	v_mad_i64_i32 v[40:41], s[30:31], s15, v252, v[112:113]
	s_lshl_b32 s30, s61, 2
	s_mov_b32 s31, s45
	v_lshl_add_u64 v[52:53], v[40:41], 0, s[30:31]
	s_lshl_b32 s30, s60, 2
	s_waitcnt vmcnt(0)
	v_lshl_add_u64 v[60:61], v[40:41], 0, s[30:31]
	global_load_dwordx4 v[32:35], v[52:53], off
	global_load_dwordx4 v[36:39], v[52:53], off offset:16
	global_load_dwordx4 v[40:43], v[60:61], off
	global_load_dwordx4 v[44:47], v[60:61], off offset:16
	global_load_dwordx4 v[48:51], v[52:53], off offset:2048
	s_nop 0
	global_load_dwordx4 v[52:55], v[52:53], off offset:2064
	s_nop 0
	global_load_dwordx4 v[56:59], v[60:61], off offset:2048
	s_nop 0
	global_load_dwordx4 v[60:63], v[60:61], off offset:2064
	s_waitcnt vmcnt(0)
	s_mov_b32 s68, s15
.LBB0_106:
	v_pk_mul_f32 v[72:73], v[72:73], v[96:97] op_sel_hi:[1,0]
	s_mov_b64 s[30:31], -1
	v_pk_fma_f32 v[84:85], v[4:5], v[72:73], v[12:13]
	v_pk_mul_f32 v[72:73], v[74:75], v[96:97] op_sel_hi:[1,0]
	v_pk_mul_f32 v[74:75], v[94:95], v[96:97] op_sel_hi:[1,0]
	v_pk_fma_f32 v[86:87], v[6:7], v[72:73], v[14:15]
	v_pk_mul_f32 v[72:73], v[76:77], v[96:97] op_sel_hi:[1,0]
	v_pk_fma_f32 v[74:75], v[18:19], v[74:75], v[26:27]
	v_pk_fma_f32 v[80:81], v[0:1], v[72:73], v[8:9]
	v_pk_mul_f32 v[72:73], v[78:79], v[96:97] op_sel_hi:[1,0]
	s_and_b64 vcc, exec, s[6:7]
	v_pk_fma_f32 v[82:83], v[2:3], v[72:73], v[10:11]
	v_pk_mul_f32 v[72:73], v[88:89], v[96:97] op_sel_hi:[1,0]
	s_nop 0
	v_pk_fma_f32 v[76:77], v[20:21], v[72:73], v[28:29]
	v_pk_mul_f32 v[72:73], v[90:91], v[96:97] op_sel_hi:[1,0]
	s_nop 0
	v_pk_fma_f32 v[78:79], v[22:23], v[72:73], v[30:31]
	v_pk_mul_f32 v[72:73], v[92:93], v[96:97] op_sel_hi:[1,0]
	s_nop 0
	v_pk_fma_f32 v[72:73], v[16:17], v[72:73], v[24:25]
	s_cbranch_vccz .LBB0_112
	s_cmp_gt_i32 s44, -1
	s_cselect_b64 s[34:35], -1, 0
	s_lshl_b64 s[30:31], s[44:45], 11
	s_nop 0
	v_pk_add_f32 v[88:89], v[40:41], 1.0 op_sel_hi:[1,0]
	v_pk_add_f32 v[90:91], v[42:43], 1.0 op_sel_hi:[1,0]
	s_nop 0
	v_pk_add_f32 v[92:93], v[44:45], 1.0 op_sel_hi:[1,0]
	v_pk_add_f32 v[94:95], v[46:47], 1.0 op_sel_hi:[1,0]
	s_add_u32 s30, s62, s30
	v_pk_fma_f32 v[88:89], v[84:85], v[88:89], v[32:33]
	v_pk_fma_f32 v[90:91], v[86:87], v[90:91], v[34:35]
	v_pk_fma_f32 v[92:93], v[80:81], v[92:93], v[36:37]
	v_pk_fma_f32 v[94:95], v[82:83], v[94:95], v[38:39]
	s_addc_u32 s31, s63, s31
	s_cmp_lt_i32 s44, 0
	v_cvt_pk_bf16_f32 v88, v88, v89
	v_cvt_pk_bf16_f32 v89, v90, v91
	v_cvt_pk_bf16_f32 v90, v92, v93
	v_cvt_pk_bf16_f32 v91, v94, v95
	v_lshl_add_u64 v[92:93], v[114:115], 0, s[28:29]
	global_store_dwordx4 v[92:93], v[88:91], off
	s_cbranch_scc1 .LBB0_109
	v_lshlrev_b32_e32 v94, 1, v108
	global_store_dwordx4 v94, v[88:91], s[30:31]
.LBB0_109:
	s_nop 0
	s_nop 0
	v_pk_add_f32 v[88:89], v[56:57], 1.0 op_sel_hi:[1,0]
	v_pk_add_f32 v[90:91], v[58:59], 1.0 op_sel_hi:[1,0]
	s_nop 0
	v_pk_add_f32 v[94:95], v[60:61], 1.0 op_sel_hi:[1,0]
	v_pk_add_f32 v[96:97], v[62:63], 1.0 op_sel_hi:[1,0]
	v_pk_fma_f32 v[88:89], v[76:77], v[88:89], v[48:49]
	v_pk_fma_f32 v[90:91], v[78:79], v[90:91], v[50:51]
	v_pk_fma_f32 v[94:95], v[72:73], v[94:95], v[52:53]
	v_pk_fma_f32 v[96:97], v[74:75], v[96:97], v[54:55]
	v_cvt_pk_bf16_f32 v88, v88, v89
	v_cvt_pk_bf16_f32 v89, v90, v91
	v_cvt_pk_bf16_f32 v90, v94, v95
	v_cvt_pk_bf16_f32 v91, v96, v97
	s_andn2_b64 vcc, exec, s[34:35]
	global_store_dwordx4 v[92:93], v[88:91], off offset:1024
	s_cbranch_vccnz .LBB0_111
	v_lshlrev_b32_e32 v92, 1, v108
	global_store_dwordx4 v92, v[88:91], s[30:31] offset:1024

.LBB0_114:
	s_nop 0
	s_nop 0
	v_lshlrev_b32_e32 v74, 16, v68
	v_and_b32_e32 v75, 0xffff0000, v68
	v_add_f32_e32 v68, 0, v74
	v_add_f32_e32 v72, v68, v75
	v_lshlrev_b32_e32 v68, 16, v69
	v_and_b32_e32 v69, 0xffff0000, v69
	v_add_f32_e32 v72, v72, v68
	v_add_f32_e32 v72, v72, v69
	v_lshlrev_b32_e32 v76, 16, v70
	v_and_b32_e32 v77, 0xffff0000, v70
	v_add_f32_e32 v70, v72, v76
	v_add_f32_e32 v72, v70, v77
	v_lshlrev_b32_e32 v70, 16, v71
	v_and_b32_e32 v71, 0xffff0000, v71
	v_add_f32_e32 v72, v72, v70
	v_add_f32_e32 v72, v72, v71
	s_nop 0
	v_lshlrev_b32_e32 v78, 16, v64
	v_and_b32_e32 v79, 0xffff0000, v64
	v_add_f32_e32 v64, v72, v78
	v_add_f32_e32 v64, v64, v79
	v_lshlrev_b32_e32 v82, 16, v65
	v_and_b32_e32 v83, 0xffff0000, v65
	v_add_f32_e32 v64, v64, v82
	v_add_f32_e32 v64, v64, v83
	v_lshlrev_b32_e32 v84, 16, v66
	v_and_b32_e32 v85, 0xffff0000, v66
	v_add_f32_e32 v64, v64, v84
	v_add_f32_e32 v64, v64, v85
	v_lshlrev_b32_e32 v86, 16, v67
	v_and_b32_e32 v87, 0xffff0000, v67
	v_add_f32_e32 v64, v64, v86
	v_add_f32_e32 v64, v64, v87
	s_nop 1
	v_add_f32_dpp v64, v64, v64 quad_perm:[1,0,3,2] row_mask:0xf bank_mask:0xf
	s_nop 1
	v_add_f32_dpp v64, v64, v64 quad_perm:[2,3,0,1] row_mask:0xf bank_mask:0xf
	s_nop 1
	v_add_f32_dpp v64, v64, v64 row_half_mirror row_mask:0xf bank_mask:0xf
	s_nop 1
	v_add_f32_dpp v64, v64, v64 row_mirror row_mask:0xf bank_mask:0xf
	v_mov_b32_e32 v65, v64
	s_nop 1
	v_permlane16_swap_b32_e32 v65, v64
	v_add_f32_e32 v64, v64, v65
	v_mov_b32_e32 v65, v64
	s_nop 1
	v_permlane32_swap_b32_e32 v65, v64
	v_add_f32_e32 v64, v64, v65
	v_mul_f32_e32 v72, 0x3a800000, v64
	v_pk_add_f32 v[64:65], v[74:75], v[72:73] op_sel_hi:[1,0] neg_lo:[0,1] neg_hi:[0,1]
	v_pk_add_f32 v[66:67], v[68:69], v[72:73] op_sel_hi:[1,0] neg_lo:[0,1] neg_hi:[0,1]
	v_pk_mul_f32 v[74:75], v[64:65], v[64:65]
	v_pk_add_f32 v[68:69], v[76:77], v[72:73] op_sel_hi:[1,0] neg_lo:[0,1] neg_hi:[0,1]
	v_pk_add_f32 v[70:71], v[70:71], v[72:73] op_sel_hi:[1,0] neg_lo:[0,1] neg_hi:[0,1]
	v_pk_add_f32 v[80:81], v[78:79], v[72:73] op_sel_hi:[1,0] neg_lo:[0,1] neg_hi:[0,1]
	v_pk_add_f32 v[82:83], v[82:83], v[72:73] op_sel_hi:[1,0] neg_lo:[0,1] neg_hi:[0,1]
	v_pk_mul_f32 v[76:77], v[66:67], v[66:67]
	v_pk_add_f32 v[84:85], v[84:85], v[72:73] op_sel_hi:[1,0] neg_lo:[0,1] neg_hi:[0,1]
	v_pk_add_f32 v[86:87], v[86:87], v[72:73] op_sel_hi:[1,0] neg_lo:[0,1] neg_hi:[0,1]
	v_add_f32_e32 v73, v74, v75
	v_add_f32_e32 v73, v76, v73
	v_pk_mul_f32 v[78:79], v[68:69], v[68:69]
	v_add_f32_e32 v73, v77, v73
	v_add_f32_e32 v73, v78, v73
	v_pk_mul_f32 v[88:89], v[70:71], v[70:71]
	v_add_f32_e32 v73, v79, v73
	v_add_f32_e32 v73, v88, v73
	v_pk_mul_f32 v[90:91], v[80:81], v[80:81]
	v_add_f32_e32 v73, v89, v73
	v_add_f32_e32 v73, v90, v73
	v_pk_mul_f32 v[92:93], v[82:83], v[82:83]
	v_add_f32_e32 v73, v91, v73
	v_add_f32_e32 v73, v92, v73
	v_pk_mul_f32 v[94:95], v[84:85], v[84:85]
	v_add_f32_e32 v73, v93, v73
	v_add_f32_e32 v73, v94, v73
	v_pk_mul_f32 v[96:97], v[86:87], v[86:87]
	v_add_f32_e32 v73, v95, v73
	v_add_f32_e32 v73, v96, v73
	v_add_f32_e32 v73, v97, v73
	s_nop 1
	v_add_f32_dpp v73, v73, v73 quad_perm:[1,0,3,2] row_mask:0xf bank_mask:0xf
	s_nop 1
	v_add_f32_dpp v73, v73, v73 quad_perm:[2,3,0,1] row_mask:0xf bank_mask:0xf
	s_nop 1
	v_add_f32_dpp v73, v73, v73 row_half_mirror row_mask:0xf bank_mask:0xf
	s_nop 1
	v_add_f32_dpp v73, v73, v73 row_mirror row_mask:0xf bank_mask:0xf
	v_mov_b32_e32 v74, v73
	s_nop 1
	v_permlane16_swap_b32_e32 v74, v73
	v_add_f32_e32 v73, v73, v74
	v_mov_b32_e32 v74, v73
	s_nop 1
	v_permlane32_swap_b32_e32 v74, v73
	v_add_f32_e32 v73, v73, v74
	v_fmamk_f32 v73, v73, 0x3a800000, v225
	v_mul_f32_e32 v74, 0x4b800000, v73
	v_cmp_gt_f32_e32 vcc, s54, v73
	s_nop 1
	v_cndmask_b32_e32 v73, v73, v74, vcc
	v_rsq_f32_e32 v73, v73
	s_nop 0
	v_mul_f32_e32 v74, 0x45800000, v73
	v_cndmask_b32_e32 v88, v73, v74, vcc
	s_and_saveexec_b64 s[24:25], s[12:13]
	s_cbranch_execz .LBB0_116
	s_lshl_b64 s[22:23], s[22:23], 3
	s_add_u32 s22, s64, s22
	v_mov_b32_e32 v73, v88
	s_addc_u32 s23, s65, s23
	global_store_dwordx2 v193, v[72:73], s[22:23]

.LBB0_123:
	s_and_b64 vcc, exec, s[4:5]
	s_cbranch_vccnz .LBB0_126
	s_cmpk_gt_i32 s18, 0xff
	s_cselect_b32 s4, s14, 32
	s_cmp_eq_u32 s4, s68
	s_cbranch_scc1 .LBB0_126
	v_mad_i64_i32 v[40:41], s[22:23], s4, v252, v[112:113]
	s_lshl_b32 s22, s61, 2
	s_mov_b32 s23, s45
	v_lshl_add_u64 v[52:53], v[40:41], 0, s[22:23]
	s_lshl_b32 s22, s60, 2
	v_lshl_add_u64 v[60:61], v[40:41], 0, s[22:23]
	global_load_dwordx4 v[32:35], v[52:53], off
	global_load_dwordx4 v[36:39], v[52:53], off offset:16
	global_load_dwordx4 v[40:43], v[60:61], off
	global_load_dwordx4 v[44:47], v[60:61], off offset:16
	global_load_dwordx4 v[48:51], v[52:53], off offset:2048
	s_nop 0
	global_load_dwordx4 v[52:55], v[52:53], off offset:2064
	s_nop 0
	global_load_dwordx4 v[56:59], v[60:61], off offset:2048
	s_nop 0
	global_load_dwordx4 v[60:63], v[60:61], off offset:2064
	s_waitcnt vmcnt(0)
	s_mov_b32 s68, s4
.LBB0_126:
	s_waitcnt vmcnt(0)
	v_pk_mul_f32 v[64:65], v[64:65], v[88:89] op_sel_hi:[1,0]
	s_mov_b64 s[4:5], -1
	v_pk_fma_f32 v[76:77], v[4:5], v[64:65], v[12:13]
	v_pk_mul_f32 v[64:65], v[66:67], v[88:89] op_sel_hi:[1,0]
	v_pk_mul_f32 v[66:67], v[86:87], v[88:89] op_sel_hi:[1,0]
	v_pk_fma_f32 v[78:79], v[6:7], v[64:65], v[14:15]
	v_pk_mul_f32 v[64:65], v[68:69], v[88:89] op_sel_hi:[1,0]
	v_pk_fma_f32 v[66:67], v[18:19], v[66:67], v[26:27]
	v_pk_fma_f32 v[72:73], v[0:1], v[64:65], v[8:9]
	v_pk_mul_f32 v[64:65], v[70:71], v[88:89] op_sel_hi:[1,0]
	s_and_b64 vcc, exec, s[6:7]
	v_pk_fma_f32 v[74:75], v[2:3], v[64:65], v[10:11]
	v_pk_mul_f32 v[64:65], v[80:81], v[88:89] op_sel_hi:[1,0]
	s_nop 0
	v_pk_fma_f32 v[68:69], v[20:21], v[64:65], v[28:29]
	v_pk_mul_f32 v[64:65], v[82:83], v[88:89] op_sel_hi:[1,0]
	s_nop 0
	v_pk_fma_f32 v[70:71], v[22:23], v[64:65], v[30:31]
	v_pk_mul_f32 v[64:65], v[84:85], v[88:89] op_sel_hi:[1,0]
	s_nop 0
	v_pk_fma_f32 v[64:65], v[16:17], v[64:65], v[24:25]
	s_cbranch_vccz .LBB0_132
	s_cmp_gt_i32 s44, -1
	s_cselect_b64 s[22:23], -1, 0
	s_lshl_b64 s[4:5], s[44:45], 11
	s_nop 0
	v_pk_add_f32 v[80:81], v[40:41], 1.0 op_sel_hi:[1,0]
	v_pk_add_f32 v[82:83], v[42:43], 1.0 op_sel_hi:[1,0]
	s_nop 0
	v_pk_add_f32 v[84:85], v[44:45], 1.0 op_sel_hi:[1,0]
	v_pk_add_f32 v[86:87], v[46:47], 1.0 op_sel_hi:[1,0]
	s_add_u32 s4, s62, s4
	v_pk_fma_f32 v[80:81], v[76:77], v[80:81], v[32:33]
	v_pk_fma_f32 v[82:83], v[78:79], v[82:83], v[34:35]
	v_pk_fma_f32 v[84:85], v[72:73], v[84:85], v[36:37]
	v_pk_fma_f32 v[86:87], v[74:75], v[86:87], v[38:39]
	s_addc_u32 s5, s63, s5
	s_cmp_lt_i32 s44, 0
	v_cvt_pk_bf16_f32 v80, v80, v81
	v_cvt_pk_bf16_f32 v81, v82, v83
	v_cvt_pk_bf16_f32 v82, v84, v85
	v_cvt_pk_bf16_f32 v83, v86, v87
	v_lshl_add_u64 v[84:85], v[114:115], 0, s[20:21]
	v_lshlrev_b32_e32 v86, 1, v108
	global_store_dwordx4 v[84:85], v[80:83], off
	s_cbranch_scc1 .LBB0_129
	global_store_dwordx4 v86, v[80:83], s[4:5]
.LBB0_129:
	s_nop 0
	s_nop 0
	v_pk_add_f32 v[80:81], v[56:57], 1.0 op_sel_hi:[1,0]
	v_pk_add_f32 v[82:83], v[58:59], 1.0 op_sel_hi:[1,0]
	s_nop 0
	v_pk_add_f32 v[88:89], v[60:61], 1.0 op_sel_hi:[1,0]
	v_pk_add_f32 v[90:91], v[62:63], 1.0 op_sel_hi:[1,0]
	v_pk_fma_f32 v[80:81], v[68:69], v[80:81], v[48:49]
	v_pk_fma_f32 v[82:83], v[70:71], v[82:83], v[50:51]
	v_pk_fma_f32 v[88:89], v[64:65], v[88:89], v[52:53]
	v_pk_fma_f32 v[90:91], v[66:67], v[90:91], v[54:55]
	v_cvt_pk_bf16_f32 v80, v80, v81
	v_cvt_pk_bf16_f32 v81, v82, v83
	v_cvt_pk_bf16_f32 v82, v88, v89
	v_cvt_pk_bf16_f32 v83, v90, v91
	s_andn2_b64 vcc, exec, s[22:23]
	global_store_dwordx4 v[84:85], v[80:83], off offset:1024
	s_cbranch_vccnz .LBB0_131
	global_store_dwordx4 v86, v[80:83], s[4:5] offset:1024
